# nt also on W_out/W_glu bf16 copy stores (phase A), layer-1 delta reads and h1 write-back (phase B)
# speedup vs baseline: 1.0161x; 1.0075x over previous
.LBB0_41:
	s_cmpk_gt_i32 s2, 0x33ff
	s_mov_b64 s[4:5], -1
	s_cbranch_scc0 .LBB0_57
	s_cmpk_gt_u32 s2, 0x343f
	s_cbranch_scc0 .LBB0_48
	s_cmpk_gt_u32 s2, 0x443f
	s_cbranch_scc0 .LBB0_45
	s_lshl_b32 s0, s2, 6
	s_lshl_b32 s4, s2, 2
	s_and_b32 s0, s0, 0x3c0
	s_and_b32 s4, s4, 0x7fffffc0
	s_add_i32 s88, s4, 0xfffeef00
	v_or_b32_e32 v17, s0, v9
	v_or_b32_e32 v28, s88, v11
	v_lshlrev_b32_e32 v194, 2, v17
	v_lshl_add_u64 v[32:33], s[46:47], 0, v[194:195]
	v_or_b32_e32 v194, 4, v28
	v_lshlrev_b64 v[26:27], 12, v[194:195]
	v_or_b32_e32 v194, 8, v28
	v_lshlrev_b64 v[68:69], 12, v[194:195]
	v_or_b32_e32 v194, 12, v28
	v_lshlrev_b64 v[70:71], 12, v[194:195]
	v_or_b32_e32 v194, 16, v28
	v_lshlrev_b64 v[76:77], 12, v[194:195]
	v_or_b32_e32 v194, 20, v28
	v_lshlrev_b64 v[78:79], 12, v[194:195]
	v_or_b32_e32 v194, 24, v28
	v_lshlrev_b64 v[84:85], 12, v[194:195]
	v_or_b32_e32 v194, 28, v28
	v_lshlrev_b64 v[86:87], 12, v[194:195]
	v_or_b32_e32 v194, 32, v28
	v_lshlrev_b64 v[92:93], 12, v[194:195]
	v_or_b32_e32 v194, 36, v28
	v_lshlrev_b64 v[94:95], 12, v[194:195]
	v_or_b32_e32 v194, 40, v28
	v_lshlrev_b64 v[100:101], 12, v[194:195]
	v_or_b32_e32 v194, 44, v28
	v_lshlrev_b64 v[102:103], 12, v[194:195]
	v_or_b32_e32 v194, 48, v28
	v_lshlrev_b64 v[108:109], 12, v[194:195]
	v_or_b32_e32 v194, 52, v28
	v_mov_b32_e32 v29, v195
	v_lshlrev_b64 v[110:111], 12, v[194:195]
	v_or_b32_e32 v194, 56, v28
	v_lshlrev_b64 v[24:25], 12, v[28:29]
	v_lshlrev_b64 v[116:117], 12, v[194:195]
	v_or_b32_e32 v194, 60, v28
	v_lshl_add_u64 v[24:25], v[32:33], 0, v[24:25]
	v_lshl_add_u64 v[64:65], v[32:33], 0, v[26:27]
	v_lshl_add_u64 v[68:69], v[32:33], 0, v[68:69]
	v_lshl_add_u64 v[72:73], v[32:33], 0, v[70:71]
	v_lshl_add_u64 v[76:77], v[32:33], 0, v[76:77]
	v_lshl_add_u64 v[80:81], v[32:33], 0, v[78:79]
	v_lshl_add_u64 v[84:85], v[32:33], 0, v[84:85]
	v_lshl_add_u64 v[88:89], v[32:33], 0, v[86:87]
	v_lshl_add_u64 v[92:93], v[32:33], 0, v[92:93]
	v_lshl_add_u64 v[96:97], v[32:33], 0, v[94:95]
	v_lshl_add_u64 v[100:101], v[32:33], 0, v[100:101]
	v_lshl_add_u64 v[104:105], v[32:33], 0, v[102:103]
	v_lshl_add_u64 v[108:109], v[32:33], 0, v[108:109]
	v_lshl_add_u64 v[112:113], v[32:33], 0, v[110:111]
	v_lshl_add_u64 v[116:117], v[32:33], 0, v[116:117]
	v_lshlrev_b64 v[28:29], 12, v[194:195]
	global_load_dwordx4 v[24:27], v[24:25], off nt
	s_nop 0
	global_load_dwordx4 v[64:67], v[64:65], off nt
	s_nop 0
	global_load_dwordx4 v[68:71], v[68:69], off nt
	s_nop 0
	global_load_dwordx4 v[72:75], v[72:73], off nt
	s_nop 0
	global_load_dwordx4 v[76:79], v[76:77], off nt
	s_nop 0
	global_load_dwordx4 v[80:83], v[80:81], off nt
	s_nop 0
	global_load_dwordx4 v[84:87], v[84:85], off nt
	s_nop 0
	global_load_dwordx4 v[88:91], v[88:89], off nt
	s_nop 0
	global_load_dwordx4 v[92:95], v[92:93], off nt
	s_nop 0
	global_load_dwordx4 v[96:99], v[96:97], off nt
	s_nop 0
	global_load_dwordx4 v[100:103], v[100:101], off nt
	s_nop 0
	global_load_dwordx4 v[104:107], v[104:105], off nt
	s_nop 0
	global_load_dwordx4 v[108:111], v[108:109], off nt
	s_nop 0
	global_load_dwordx4 v[112:115], v[112:113], off nt
	v_lshl_add_u64 v[28:29], v[32:33], 0, v[28:29]
	global_load_dwordx4 v[116:119], v[116:117], off nt
	s_nop 0
	global_load_dwordx4 v[120:123], v[28:29], off nt
	v_add_u32_e32 v17, v31, v34
	v_add_u32_e32 v19, v31, v35
	v_add_u32_e32 v21, v31, v36
	v_add_u32_e32 v23, v31, v37
	v_add_u32_e32 v28, v31, v38
	v_add_u32_e32 v29, v31, v39
	v_add_u32_e32 v30, v31, v40
	v_add_u32_e32 v32, v31, v41
	s_mov_b64 s[4:5], 0
	s_waitcnt vmcnt(15)
	ds_write_b128 v17, v[24:27]
	s_waitcnt vmcnt(14)
	ds_write_b128 v17, v[64:67] offset:1088
	s_waitcnt vmcnt(13)
	ds_write_b128 v19, v[68:71] offset:2176
	s_waitcnt vmcnt(12)
	ds_write_b128 v19, v[72:75] offset:3264
	s_waitcnt vmcnt(11)
	ds_write_b128 v21, v[76:79] offset:4352
	s_waitcnt vmcnt(10)
	ds_write_b128 v21, v[80:83] offset:5440
	s_waitcnt vmcnt(9)
	ds_write_b128 v23, v[84:87] offset:6528
	s_waitcnt vmcnt(8)
	ds_write_b128 v23, v[88:91] offset:7616
	s_waitcnt vmcnt(7)
	ds_write_b128 v28, v[92:95] offset:8704
	s_waitcnt vmcnt(6)
	ds_write_b128 v28, v[96:99] offset:9792
	s_waitcnt vmcnt(5)
	ds_write_b128 v29, v[100:103] offset:10880
	s_waitcnt vmcnt(4)
	ds_write_b128 v29, v[104:107] offset:11968
	s_waitcnt vmcnt(3)
	ds_write_b128 v30, v[108:111] offset:13056
	s_waitcnt vmcnt(2)
	ds_write_b128 v30, v[112:115] offset:14144
	s_waitcnt vmcnt(1)
	ds_write_b128 v32, v[116:119] offset:15232
	s_waitcnt vmcnt(0)
	ds_write_b128 v32, v[120:123] offset:16320
	s_waitcnt lgkmcnt(0)
	ds_read2_b32 v[26:27], v43 offset1:68
	ds_read2_b32 v[28:29], v43 offset0:136 offset1:204
	v_add_u32_e32 v17, 0x400, v43
	ds_read2_b32 v[32:33], v17 offset0:16 offset1:84
	ds_read2_b32 v[64:65], v17 offset0:152 offset1:220
	s_waitcnt lgkmcnt(3)
	v_bfe_u32 v19, v26, 16, 1
	v_bfe_u32 v21, v27, 16, 1
	v_add3_u32 v19, v26, v19, s22
	s_waitcnt lgkmcnt(2)
	v_bfe_u32 v23, v28, 16, 1
	v_add3_u32 v21, v27, v21, s22
	v_lshrrev_b32_e32 v19, 16, v19
	v_add3_u32 v23, v28, v23, s22
	v_and_or_b32 v26, v21, s23, v19
	v_bfe_u32 v19, v29, 16, 1
	v_lshrrev_b32_e32 v23, 16, v23
	v_add3_u32 v19, v29, v19, s22
	v_and_or_b32 v27, v19, s23, v23
	s_waitcnt lgkmcnt(1)
	v_bfe_u32 v19, v32, 16, 1
	v_add3_u32 v19, v32, v19, s22
	v_lshrrev_b32_e32 v17, 16, v19
	v_bfe_u32 v19, v33, 16, 1
	v_add3_u32 v19, v33, v19, s22
	v_and_or_b32 v28, v19, s23, v17
	s_waitcnt lgkmcnt(0)
	v_bfe_u32 v17, v64, 16, 1
	ds_read2_b32 v[32:33], v45 offset1:68
	v_add3_u32 v17, v64, v17, s22
	v_bfe_u32 v19, v65, 16, 1
	v_lshrrev_b32_e32 v17, 16, v17
	v_add3_u32 v19, v65, v19, s22
	v_and_or_b32 v29, v19, s23, v17
	v_or_b32_e32 v17, s0, v42
	v_lshl_add_u64 v[24:25], s[88:89], 1, v[2:3]
	v_lshlrev_b32_e32 v194, 11, v17
	v_lshl_add_u64 v[64:65], v[24:25], 0, v[194:195]
	s_waitcnt lgkmcnt(0)
	v_bfe_u32 v17, v32, 16, 1
	global_store_dwordx4 v[64:65], v[26:29], off nt
	v_add3_u32 v17, v32, v17, s22
	ds_read2_b32 v[28:29], v45 offset0:136 offset1:204
	v_bfe_u32 v19, v33, 16, 1
	v_lshrrev_b32_e32 v17, 16, v17
	v_add3_u32 v19, v33, v19, s22
	v_and_or_b32 v26, v19, s23, v17
	v_add_u32_e32 v19, 0x400, v45
	ds_read2_b32 v[32:33], v19 offset0:16 offset1:84
	s_waitcnt lgkmcnt(1)
	v_bfe_u32 v17, v28, 16, 1
	v_add3_u32 v17, v28, v17, s22
	v_bfe_u32 v21, v29, 16, 1
	ds_read2_b32 v[64:65], v19 offset0:152 offset1:220
	v_lshrrev_b32_e32 v17, 16, v17
	v_add3_u32 v21, v29, v21, s22
	v_and_or_b32 v27, v21, s23, v17
	s_waitcnt lgkmcnt(1)
	v_bfe_u32 v17, v32, 16, 1
	v_add3_u32 v17, v32, v17, s22
	v_bfe_u32 v19, v33, 16, 1
	v_lshrrev_b32_e32 v17, 16, v17
	v_add3_u32 v19, v33, v19, s22
	v_and_or_b32 v28, v19, s23, v17
	s_waitcnt lgkmcnt(0)
	v_bfe_u32 v17, v64, 16, 1
	ds_read2_b32 v[32:33], v47 offset1:68
	v_add3_u32 v17, v64, v17, s22
	v_bfe_u32 v19, v65, 16, 1
	v_lshrrev_b32_e32 v17, 16, v17
	v_add3_u32 v19, v65, v19, s22
	v_and_or_b32 v29, v19, s23, v17
	v_or_b32_e32 v17, s0, v44
	v_lshlrev_b32_e32 v194, 11, v17
	v_lshl_add_u64 v[64:65], v[24:25], 0, v[194:195]
	s_waitcnt lgkmcnt(0)
	v_bfe_u32 v17, v32, 16, 1
	global_store_dwordx4 v[64:65], v[26:29], off nt
	v_add3_u32 v17, v32, v17, s22
	ds_read2_b32 v[28:29], v47 offset0:136 offset1:204
	v_bfe_u32 v19, v33, 16, 1
	v_lshrrev_b32_e32 v17, 16, v17
	v_add3_u32 v19, v33, v19, s22
	v_and_or_b32 v26, v19, s23, v17
	v_add_u32_e32 v19, 0x400, v47
	ds_read2_b32 v[32:33], v19 offset0:16 offset1:84
	s_waitcnt lgkmcnt(1)
	v_bfe_u32 v17, v28, 16, 1
	v_add3_u32 v17, v28, v17, s22
	v_bfe_u32 v21, v29, 16, 1
	ds_read2_b32 v[64:65], v19 offset0:152 offset1:220
	v_lshrrev_b32_e32 v17, 16, v17
	v_add3_u32 v21, v29, v21, s22
	v_and_or_b32 v27, v21, s23, v17
	s_waitcnt lgkmcnt(1)
	v_bfe_u32 v17, v32, 16, 1
	v_add3_u32 v17, v32, v17, s22
	v_bfe_u32 v19, v33, 16, 1
	v_lshrrev_b32_e32 v17, 16, v17
	v_add3_u32 v19, v33, v19, s22
	v_and_or_b32 v28, v19, s23, v17
	s_waitcnt lgkmcnt(0)
	v_bfe_u32 v17, v64, 16, 1
	ds_read2_b32 v[32:33], v49 offset1:68
	v_add3_u32 v17, v64, v17, s22
	v_bfe_u32 v19, v65, 16, 1
	v_lshrrev_b32_e32 v17, 16, v17
	v_add3_u32 v19, v65, v19, s22
	v_and_or_b32 v29, v19, s23, v17
	v_or_b32_e32 v17, s0, v46
	v_lshlrev_b32_e32 v194, 11, v17
	v_lshl_add_u64 v[64:65], v[24:25], 0, v[194:195]
	s_waitcnt lgkmcnt(0)
	v_bfe_u32 v17, v32, 16, 1
	global_store_dwordx4 v[64:65], v[26:29], off nt
	v_add3_u32 v17, v32, v17, s22
	ds_read2_b32 v[28:29], v49 offset0:136 offset1:204
	v_bfe_u32 v19, v33, 16, 1
	v_lshrrev_b32_e32 v17, 16, v17
	v_add3_u32 v19, v33, v19, s22
	v_and_or_b32 v26, v19, s23, v17
	v_add_u32_e32 v19, 0x400, v49
	ds_read2_b32 v[32:33], v19 offset0:16 offset1:84
	s_waitcnt lgkmcnt(1)
	v_bfe_u32 v17, v28, 16, 1
	v_add3_u32 v17, v28, v17, s22
	v_bfe_u32 v21, v29, 16, 1
	ds_read2_b32 v[64:65], v19 offset0:152 offset1:220
	v_lshrrev_b32_e32 v17, 16, v17
	v_add3_u32 v21, v29, v21, s22
	v_and_or_b32 v27, v21, s23, v17
	s_waitcnt lgkmcnt(1)
	v_bfe_u32 v17, v32, 16, 1
	v_add3_u32 v17, v32, v17, s22
	v_bfe_u32 v19, v33, 16, 1
	v_lshrrev_b32_e32 v17, 16, v17
	v_add3_u32 v19, v33, v19, s22
	v_and_or_b32 v28, v19, s23, v17
	s_waitcnt lgkmcnt(0)
	v_bfe_u32 v17, v64, 16, 1
	ds_read2_b32 v[32:33], v51 offset1:68
	v_add3_u32 v17, v64, v17, s22
	v_bfe_u32 v19, v65, 16, 1
	v_lshrrev_b32_e32 v17, 16, v17
	v_add3_u32 v19, v65, v19, s22
	v_and_or_b32 v29, v19, s23, v17
	v_or_b32_e32 v17, s0, v48
	v_lshlrev_b32_e32 v194, 11, v17
	v_lshl_add_u64 v[64:65], v[24:25], 0, v[194:195]
	s_waitcnt lgkmcnt(0)
	v_bfe_u32 v17, v32, 16, 1
	global_store_dwordx4 v[64:65], v[26:29], off nt
	v_add3_u32 v17, v32, v17, s22
	ds_read2_b32 v[28:29], v51 offset0:136 offset1:204
	v_bfe_u32 v19, v33, 16, 1
	v_lshrrev_b32_e32 v17, 16, v17
	v_add3_u32 v19, v33, v19, s22
	v_and_or_b32 v26, v19, s23, v17
	v_add_u32_e32 v19, 0x400, v51
	ds_read2_b32 v[32:33], v19 offset0:16 offset1:84
	s_waitcnt lgkmcnt(1)
	v_bfe_u32 v17, v28, 16, 1
	v_add3_u32 v17, v28, v17, s22
	v_bfe_u32 v21, v29, 16, 1
	ds_read2_b32 v[64:65], v19 offset0:152 offset1:220
	v_lshrrev_b32_e32 v17, 16, v17
	v_add3_u32 v21, v29, v21, s22
	v_and_or_b32 v27, v21, s23, v17
	s_waitcnt lgkmcnt(1)
	v_bfe_u32 v17, v32, 16, 1
	v_add3_u32 v17, v32, v17, s22
	v_bfe_u32 v19, v33, 16, 1
	v_lshrrev_b32_e32 v17, 16, v17
	v_add3_u32 v19, v33, v19, s22
	v_and_or_b32 v28, v19, s23, v17
	s_waitcnt lgkmcnt(0)
	v_bfe_u32 v17, v64, 16, 1
	ds_read2_b32 v[32:33], v53 offset1:68
	v_add3_u32 v17, v64, v17, s22
	v_bfe_u32 v19, v65, 16, 1
	v_lshrrev_b32_e32 v17, 16, v17
	v_add3_u32 v19, v65, v19, s22
	v_and_or_b32 v29, v19, s23, v17
	v_or_b32_e32 v17, s0, v50
	v_lshlrev_b32_e32 v194, 11, v17
	v_lshl_add_u64 v[64:65], v[24:25], 0, v[194:195]
	s_waitcnt lgkmcnt(0)
	v_bfe_u32 v17, v32, 16, 1
	global_store_dwordx4 v[64:65], v[26:29], off nt
	v_add3_u32 v17, v32, v17, s22
	ds_read2_b32 v[28:29], v53 offset0:136 offset1:204
	v_bfe_u32 v19, v33, 16, 1
	v_lshrrev_b32_e32 v17, 16, v17
	v_add3_u32 v19, v33, v19, s22
	v_and_or_b32 v26, v19, s23, v17
	v_add_u32_e32 v19, 0x400, v53
	ds_read2_b32 v[32:33], v19 offset0:16 offset1:84
	s_waitcnt lgkmcnt(1)
	v_bfe_u32 v17, v28, 16, 1
	v_add3_u32 v17, v28, v17, s22
	v_bfe_u32 v21, v29, 16, 1
	ds_read2_b32 v[64:65], v19 offset0:152 offset1:220
	v_lshrrev_b32_e32 v17, 16, v17
	v_add3_u32 v21, v29, v21, s22
	v_and_or_b32 v27, v21, s23, v17
	s_waitcnt lgkmcnt(1)
	v_bfe_u32 v17, v32, 16, 1
	v_add3_u32 v17, v32, v17, s22
	v_bfe_u32 v19, v33, 16, 1
	v_lshrrev_b32_e32 v17, 16, v17
	v_add3_u32 v19, v33, v19, s22
	v_and_or_b32 v28, v19, s23, v17
	s_waitcnt lgkmcnt(0)
	v_bfe_u32 v17, v64, 16, 1
	ds_read2_b32 v[32:33], v55 offset1:68
	v_add3_u32 v17, v64, v17, s22
	v_bfe_u32 v19, v65, 16, 1
	v_lshrrev_b32_e32 v17, 16, v17
	v_add3_u32 v19, v65, v19, s22
	v_and_or_b32 v29, v19, s23, v17
	v_or_b32_e32 v17, s0, v52
	v_lshlrev_b32_e32 v194, 11, v17
	v_lshl_add_u64 v[64:65], v[24:25], 0, v[194:195]
	s_waitcnt lgkmcnt(0)
	v_bfe_u32 v17, v32, 16, 1
	global_store_dwordx4 v[64:65], v[26:29], off nt
	v_add3_u32 v17, v32, v17, s22
	ds_read2_b32 v[28:29], v55 offset0:136 offset1:204
	v_bfe_u32 v19, v33, 16, 1
	v_lshrrev_b32_e32 v17, 16, v17
	v_add3_u32 v19, v33, v19, s22
	v_and_or_b32 v26, v19, s23, v17
	v_add_u32_e32 v19, 0x400, v55
	ds_read2_b32 v[32:33], v19 offset0:16 offset1:84
	s_waitcnt lgkmcnt(1)
	v_bfe_u32 v17, v28, 16, 1
	v_add3_u32 v17, v28, v17, s22
	v_bfe_u32 v21, v29, 16, 1
	ds_read2_b32 v[64:65], v19 offset0:152 offset1:220
	v_lshrrev_b32_e32 v17, 16, v17
	v_add3_u32 v21, v29, v21, s22
	v_and_or_b32 v27, v21, s23, v17
	s_waitcnt lgkmcnt(1)
	v_bfe_u32 v17, v32, 16, 1
	v_add3_u32 v17, v32, v17, s22
	v_bfe_u32 v19, v33, 16, 1
	v_lshrrev_b32_e32 v17, 16, v17
	v_add3_u32 v19, v33, v19, s22
	v_and_or_b32 v28, v19, s23, v17
	s_waitcnt lgkmcnt(0)
	v_bfe_u32 v17, v64, 16, 1
	ds_read2_b32 v[32:33], v57 offset1:68
	v_add3_u32 v17, v64, v17, s22
	v_bfe_u32 v19, v65, 16, 1
	v_lshrrev_b32_e32 v17, 16, v17
	v_add3_u32 v19, v65, v19, s22
	v_and_or_b32 v29, v19, s23, v17
	v_or_b32_e32 v17, s0, v54
	v_lshlrev_b32_e32 v194, 11, v17
	v_lshl_add_u64 v[64:65], v[24:25], 0, v[194:195]
	s_waitcnt lgkmcnt(0)
	v_bfe_u32 v17, v32, 16, 1
	global_store_dwordx4 v[64:65], v[26:29], off nt
	v_add3_u32 v17, v32, v17, s22
	ds_read2_b32 v[28:29], v57 offset0:136 offset1:204
	v_bfe_u32 v19, v33, 16, 1
	v_lshrrev_b32_e32 v17, 16, v17
	v_add3_u32 v19, v33, v19, s22
	v_and_or_b32 v26, v19, s23, v17
	v_add_u32_e32 v19, 0x400, v57
	ds_read2_b32 v[32:33], v19 offset0:16 offset1:84
	s_waitcnt lgkmcnt(1)
	v_bfe_u32 v17, v28, 16, 1
	v_add3_u32 v17, v28, v17, s22
	v_bfe_u32 v21, v29, 16, 1
	ds_read2_b32 v[64:65], v19 offset0:152 offset1:220
	v_lshrrev_b32_e32 v17, 16, v17
	v_add3_u32 v21, v29, v21, s22
	v_and_or_b32 v27, v21, s23, v17
	s_waitcnt lgkmcnt(1)
	v_bfe_u32 v17, v32, 16, 1
	v_add3_u32 v17, v32, v17, s22
	v_bfe_u32 v19, v33, 16, 1
	v_lshrrev_b32_e32 v17, 16, v17
	v_add3_u32 v19, v33, v19, s22
	v_and_or_b32 v28, v19, s23, v17
	s_waitcnt lgkmcnt(0)
	v_bfe_u32 v17, v64, 16, 1
	v_add3_u32 v17, v64, v17, s22
	v_bfe_u32 v19, v65, 16, 1
	v_lshrrev_b32_e32 v17, 16, v17
	v_add3_u32 v19, v65, v19, s22
	v_and_or_b32 v29, v19, s23, v17
	v_or_b32_e32 v17, s0, v56
	v_lshlrev_b32_e32 v194, 11, v17
	v_lshl_add_u64 v[24:25], v[24:25], 0, v[194:195]
	global_store_dwordx4 v[24:25], v[26:29], off nt
	s_waitcnt lgkmcnt(0)
.LBB0_45:
	s_andn2_b64 vcc, exec, s[4:5]
	s_cbranch_vccnz .LBB0_47
	s_and_b32 s0, s2, 0x7fc0
	s_add_i32 s88, s0, 0xffffcbc0
	s_lshl_b32 s0, s2, 6
	s_and_b32 s0, s0, 0xfc0
	v_or_b32_e32 v17, s0, v9
	v_or_b32_e32 v28, s88, v11
	v_lshlrev_b32_e32 v194, 2, v17
	v_lshl_add_u64 v[32:33], s[44:45], 0, v[194:195]
	v_or_b32_e32 v194, 4, v28
	v_lshlrev_b64 v[26:27], 14, v[194:195]
	v_or_b32_e32 v194, 8, v28
	v_lshlrev_b64 v[68:69], 14, v[194:195]
	v_or_b32_e32 v194, 12, v28
	v_lshlrev_b64 v[70:71], 14, v[194:195]
	v_or_b32_e32 v194, 16, v28
	v_lshlrev_b64 v[76:77], 14, v[194:195]
	v_or_b32_e32 v194, 20, v28
	v_lshlrev_b64 v[78:79], 14, v[194:195]
	v_or_b32_e32 v194, 24, v28
	v_lshlrev_b64 v[84:85], 14, v[194:195]
	v_or_b32_e32 v194, 28, v28
	v_lshlrev_b64 v[86:87], 14, v[194:195]
	v_or_b32_e32 v194, 32, v28
	v_lshlrev_b64 v[92:93], 14, v[194:195]
	v_or_b32_e32 v194, 36, v28
	v_lshlrev_b64 v[94:95], 14, v[194:195]
	v_or_b32_e32 v194, 40, v28
	v_lshlrev_b64 v[100:101], 14, v[194:195]
	v_or_b32_e32 v194, 44, v28
	v_lshlrev_b64 v[102:103], 14, v[194:195]
	v_or_b32_e32 v194, 48, v28
	v_lshlrev_b64 v[108:109], 14, v[194:195]
	v_or_b32_e32 v194, 52, v28
	v_mov_b32_e32 v29, v195
	v_lshlrev_b64 v[110:111], 14, v[194:195]
	v_or_b32_e32 v194, 56, v28
	v_lshlrev_b64 v[24:25], 14, v[28:29]
	v_lshlrev_b64 v[116:117], 14, v[194:195]
	v_or_b32_e32 v194, 60, v28
	v_lshl_add_u64 v[24:25], v[32:33], 0, v[24:25]
	v_lshl_add_u64 v[64:65], v[32:33], 0, v[26:27]
	v_lshl_add_u64 v[68:69], v[32:33], 0, v[68:69]
	v_lshl_add_u64 v[72:73], v[32:33], 0, v[70:71]
	v_lshl_add_u64 v[76:77], v[32:33], 0, v[76:77]
	v_lshl_add_u64 v[80:81], v[32:33], 0, v[78:79]
	v_lshl_add_u64 v[84:85], v[32:33], 0, v[84:85]
	v_lshl_add_u64 v[88:89], v[32:33], 0, v[86:87]
	v_lshl_add_u64 v[92:93], v[32:33], 0, v[92:93]
	v_lshl_add_u64 v[96:97], v[32:33], 0, v[94:95]
	v_lshl_add_u64 v[100:101], v[32:33], 0, v[100:101]
	v_lshl_add_u64 v[104:105], v[32:33], 0, v[102:103]
	v_lshl_add_u64 v[108:109], v[32:33], 0, v[108:109]
	v_lshl_add_u64 v[112:113], v[32:33], 0, v[110:111]
	v_lshl_add_u64 v[116:117], v[32:33], 0, v[116:117]
	v_lshlrev_b64 v[28:29], 14, v[194:195]
	global_load_dwordx4 v[24:27], v[24:25], off nt
	s_nop 0
	global_load_dwordx4 v[64:67], v[64:65], off nt
	s_nop 0
	global_load_dwordx4 v[68:71], v[68:69], off nt
	s_nop 0
	global_load_dwordx4 v[72:75], v[72:73], off nt
	s_nop 0
	global_load_dwordx4 v[76:79], v[76:77], off nt
	s_nop 0
	global_load_dwordx4 v[80:83], v[80:81], off nt
	s_nop 0
	global_load_dwordx4 v[84:87], v[84:85], off nt
	s_nop 0
	global_load_dwordx4 v[88:91], v[88:89], off nt
	s_nop 0
	global_load_dwordx4 v[92:95], v[92:93], off nt
	s_nop 0
	global_load_dwordx4 v[96:99], v[96:97], off nt
	s_nop 0
	global_load_dwordx4 v[100:103], v[100:101], off nt
	s_nop 0
	global_load_dwordx4 v[104:107], v[104:105], off nt
	s_nop 0
	global_load_dwordx4 v[108:111], v[108:109], off nt
	s_nop 0
	global_load_dwordx4 v[112:115], v[112:113], off nt
	v_lshl_add_u64 v[28:29], v[32:33], 0, v[28:29]
	global_load_dwordx4 v[116:119], v[116:117], off nt
	s_nop 0
	global_load_dwordx4 v[120:123], v[28:29], off nt
	v_add_u32_e32 v17, v31, v34
	v_add_u32_e32 v19, v31, v35
	v_add_u32_e32 v21, v31, v36
	v_add_u32_e32 v23, v31, v37
	v_add_u32_e32 v28, v31, v38
	v_add_u32_e32 v29, v31, v39
	v_add_u32_e32 v30, v31, v40
	v_add_u32_e32 v32, v31, v41
	s_waitcnt vmcnt(15)
	ds_write_b128 v17, v[24:27]
	s_waitcnt vmcnt(14)
	ds_write_b128 v17, v[64:67] offset:1088
	s_waitcnt vmcnt(13)
	ds_write_b128 v19, v[68:71] offset:2176
	s_waitcnt vmcnt(12)
	ds_write_b128 v19, v[72:75] offset:3264
	s_waitcnt vmcnt(11)
	ds_write_b128 v21, v[76:79] offset:4352
	s_waitcnt vmcnt(10)
	ds_write_b128 v21, v[80:83] offset:5440
	s_waitcnt vmcnt(9)
	ds_write_b128 v23, v[84:87] offset:6528
	s_waitcnt vmcnt(8)
	ds_write_b128 v23, v[88:91] offset:7616
	s_waitcnt vmcnt(7)
	ds_write_b128 v28, v[92:95] offset:8704
	s_waitcnt vmcnt(6)
	ds_write_b128 v28, v[96:99] offset:9792
	s_waitcnt vmcnt(5)
	ds_write_b128 v29, v[100:103] offset:10880
	s_waitcnt vmcnt(4)
	ds_write_b128 v29, v[104:107] offset:11968
	s_waitcnt vmcnt(3)
	ds_write_b128 v30, v[108:111] offset:13056
	s_waitcnt vmcnt(2)
	ds_write_b128 v30, v[112:115] offset:14144
	s_waitcnt vmcnt(1)
	ds_write_b128 v32, v[116:119] offset:15232
	s_waitcnt vmcnt(0)
	ds_write_b128 v32, v[120:123] offset:16320
	s_waitcnt lgkmcnt(0)
	ds_read2_b32 v[26:27], v43 offset1:68
	ds_read2_b32 v[28:29], v43 offset0:136 offset1:204
	v_add_u32_e32 v17, 0x400, v43
	ds_read2_b32 v[32:33], v17 offset0:16 offset1:84
	ds_read2_b32 v[64:65], v17 offset0:152 offset1:220
	s_waitcnt lgkmcnt(3)
	v_bfe_u32 v19, v26, 16, 1
	v_bfe_u32 v21, v27, 16, 1
	s_waitcnt lgkmcnt(2)
	v_bfe_u32 v23, v28, 16, 1
	v_add3_u32 v19, v26, v19, s22
	v_bfe_u32 v30, v29, 16, 1
	v_add3_u32 v21, v27, v21, s22
	v_add3_u32 v23, v28, v23, s22
	v_lshrrev_b32_e32 v19, 16, v19
	v_lshrrev_b32_e32 v23, 16, v23
	v_and_or_b32 v26, v21, s23, v19
	v_add3_u32 v19, v29, v30, s22
	v_and_or_b32 v27, v19, s23, v23
	s_waitcnt lgkmcnt(1)
	v_bfe_u32 v19, v32, 16, 1
	v_add3_u32 v19, v32, v19, s22
	v_lshrrev_b32_e32 v17, 16, v19
	v_bfe_u32 v19, v33, 16, 1
	v_add3_u32 v19, v33, v19, s22
	v_and_or_b32 v28, v19, s23, v17
	s_waitcnt lgkmcnt(0)
	v_bfe_u32 v17, v64, 16, 1
	ds_read2_b32 v[32:33], v45 offset1:68
	v_add3_u32 v17, v64, v17, s22
	v_bfe_u32 v19, v65, 16, 1
	v_lshrrev_b32_e32 v17, 16, v17
	v_add3_u32 v19, v65, v19, s22
	v_and_or_b32 v29, v19, s23, v17
	v_or_b32_e32 v17, s0, v42
	v_lshl_add_u64 v[24:25], s[88:89], 1, v[4:5]
	v_lshlrev_b32_e32 v194, 13, v17
	v_lshl_add_u64 v[64:65], v[24:25], 0, v[194:195]
	s_waitcnt lgkmcnt(0)
	v_bfe_u32 v17, v32, 16, 1
	global_store_dwordx4 v[64:65], v[26:29], off nt
	v_add3_u32 v17, v32, v17, s22
	ds_read2_b32 v[28:29], v45 offset0:136 offset1:204
	v_bfe_u32 v19, v33, 16, 1
	v_lshrrev_b32_e32 v17, 16, v17
	v_add3_u32 v19, v33, v19, s22
	v_and_or_b32 v26, v19, s23, v17
	v_add_u32_e32 v19, 0x400, v45
	ds_read2_b32 v[32:33], v19 offset0:16 offset1:84
	s_waitcnt lgkmcnt(1)
	v_bfe_u32 v17, v28, 16, 1
	v_add3_u32 v17, v28, v17, s22
	v_bfe_u32 v21, v29, 16, 1
	ds_read2_b32 v[64:65], v19 offset0:152 offset1:220
	v_lshrrev_b32_e32 v17, 16, v17
	v_add3_u32 v21, v29, v21, s22
	v_and_or_b32 v27, v21, s23, v17
	s_waitcnt lgkmcnt(1)
	v_bfe_u32 v17, v32, 16, 1
	v_add3_u32 v17, v32, v17, s22
	v_bfe_u32 v19, v33, 16, 1
	v_lshrrev_b32_e32 v17, 16, v17
	v_add3_u32 v19, v33, v19, s22
	v_and_or_b32 v28, v19, s23, v17
	s_waitcnt lgkmcnt(0)
	v_bfe_u32 v17, v64, 16, 1
	ds_read2_b32 v[32:33], v47 offset1:68
	v_add3_u32 v17, v64, v17, s22
	v_bfe_u32 v19, v65, 16, 1
	v_lshrrev_b32_e32 v17, 16, v17
	v_add3_u32 v19, v65, v19, s22
	v_and_or_b32 v29, v19, s23, v17
	v_or_b32_e32 v17, s0, v44
	v_lshlrev_b32_e32 v194, 13, v17
	v_lshl_add_u64 v[64:65], v[24:25], 0, v[194:195]
	s_waitcnt lgkmcnt(0)
	v_bfe_u32 v17, v32, 16, 1
	global_store_dwordx4 v[64:65], v[26:29], off nt
	v_add3_u32 v17, v32, v17, s22
	ds_read2_b32 v[28:29], v47 offset0:136 offset1:204
	v_bfe_u32 v19, v33, 16, 1
	v_lshrrev_b32_e32 v17, 16, v17
	v_add3_u32 v19, v33, v19, s22
	v_and_or_b32 v26, v19, s23, v17
	v_add_u32_e32 v19, 0x400, v47
	ds_read2_b32 v[32:33], v19 offset0:16 offset1:84
	s_waitcnt lgkmcnt(1)
	v_bfe_u32 v17, v28, 16, 1
	v_add3_u32 v17, v28, v17, s22
	v_bfe_u32 v21, v29, 16, 1
	ds_read2_b32 v[64:65], v19 offset0:152 offset1:220
	v_lshrrev_b32_e32 v17, 16, v17
	v_add3_u32 v21, v29, v21, s22
	v_and_or_b32 v27, v21, s23, v17
	s_waitcnt lgkmcnt(1)
	v_bfe_u32 v17, v32, 16, 1
	v_add3_u32 v17, v32, v17, s22
	v_bfe_u32 v19, v33, 16, 1
	v_lshrrev_b32_e32 v17, 16, v17
	v_add3_u32 v19, v33, v19, s22
	v_and_or_b32 v28, v19, s23, v17
	s_waitcnt lgkmcnt(0)
	v_bfe_u32 v17, v64, 16, 1
	ds_read2_b32 v[32:33], v49 offset1:68
	v_add3_u32 v17, v64, v17, s22
	v_bfe_u32 v19, v65, 16, 1
	v_lshrrev_b32_e32 v17, 16, v17
	v_add3_u32 v19, v65, v19, s22
	v_and_or_b32 v29, v19, s23, v17
	v_or_b32_e32 v17, s0, v46
	v_lshlrev_b32_e32 v194, 13, v17
	v_lshl_add_u64 v[64:65], v[24:25], 0, v[194:195]
	s_waitcnt lgkmcnt(0)
	v_bfe_u32 v17, v32, 16, 1
	global_store_dwordx4 v[64:65], v[26:29], off nt
	v_add3_u32 v17, v32, v17, s22
	ds_read2_b32 v[28:29], v49 offset0:136 offset1:204
	v_bfe_u32 v19, v33, 16, 1
	v_lshrrev_b32_e32 v17, 16, v17
	v_add3_u32 v19, v33, v19, s22
	v_and_or_b32 v26, v19, s23, v17
	v_add_u32_e32 v19, 0x400, v49
	ds_read2_b32 v[32:33], v19 offset0:16 offset1:84
	s_waitcnt lgkmcnt(1)
	v_bfe_u32 v17, v28, 16, 1
	v_add3_u32 v17, v28, v17, s22
	v_bfe_u32 v21, v29, 16, 1
	ds_read2_b32 v[64:65], v19 offset0:152 offset1:220
	v_lshrrev_b32_e32 v17, 16, v17
	v_add3_u32 v21, v29, v21, s22
	v_and_or_b32 v27, v21, s23, v17
	s_waitcnt lgkmcnt(1)
	v_bfe_u32 v17, v32, 16, 1
	v_add3_u32 v17, v32, v17, s22
	v_bfe_u32 v19, v33, 16, 1
	v_lshrrev_b32_e32 v17, 16, v17
	v_add3_u32 v19, v33, v19, s22
	v_and_or_b32 v28, v19, s23, v17
	s_waitcnt lgkmcnt(0)
	v_bfe_u32 v17, v64, 16, 1
	ds_read2_b32 v[32:33], v51 offset1:68
	v_add3_u32 v17, v64, v17, s22
	v_bfe_u32 v19, v65, 16, 1
	v_lshrrev_b32_e32 v17, 16, v17
	v_add3_u32 v19, v65, v19, s22
	v_and_or_b32 v29, v19, s23, v17
	v_or_b32_e32 v17, s0, v48
	v_lshlrev_b32_e32 v194, 13, v17
	v_lshl_add_u64 v[64:65], v[24:25], 0, v[194:195]
	s_waitcnt lgkmcnt(0)
	v_bfe_u32 v17, v32, 16, 1
	global_store_dwordx4 v[64:65], v[26:29], off nt
	v_add3_u32 v17, v32, v17, s22
	ds_read2_b32 v[28:29], v51 offset0:136 offset1:204
	v_bfe_u32 v19, v33, 16, 1
	v_lshrrev_b32_e32 v17, 16, v17
	v_add3_u32 v19, v33, v19, s22
	v_and_or_b32 v26, v19, s23, v17
	v_add_u32_e32 v19, 0x400, v51
	ds_read2_b32 v[32:33], v19 offset0:16 offset1:84
	s_waitcnt lgkmcnt(1)
	v_bfe_u32 v17, v28, 16, 1
	v_add3_u32 v17, v28, v17, s22
	v_bfe_u32 v21, v29, 16, 1
	ds_read2_b32 v[64:65], v19 offset0:152 offset1:220
	v_lshrrev_b32_e32 v17, 16, v17
	v_add3_u32 v21, v29, v21, s22
	v_and_or_b32 v27, v21, s23, v17
	s_waitcnt lgkmcnt(1)
	v_bfe_u32 v17, v32, 16, 1
	v_add3_u32 v17, v32, v17, s22
	v_bfe_u32 v19, v33, 16, 1
	v_lshrrev_b32_e32 v17, 16, v17
	v_add3_u32 v19, v33, v19, s22
	v_and_or_b32 v28, v19, s23, v17
	s_waitcnt lgkmcnt(0)
	v_bfe_u32 v17, v64, 16, 1
	ds_read2_b32 v[32:33], v53 offset1:68
	v_add3_u32 v17, v64, v17, s22
	v_bfe_u32 v19, v65, 16, 1
	v_lshrrev_b32_e32 v17, 16, v17
	v_add3_u32 v19, v65, v19, s22
	v_and_or_b32 v29, v19, s23, v17
	v_or_b32_e32 v17, s0, v50
	v_lshlrev_b32_e32 v194, 13, v17
	v_lshl_add_u64 v[64:65], v[24:25], 0, v[194:195]
	s_waitcnt lgkmcnt(0)
	v_bfe_u32 v17, v32, 16, 1
	global_store_dwordx4 v[64:65], v[26:29], off nt
	v_add3_u32 v17, v32, v17, s22
	ds_read2_b32 v[28:29], v53 offset0:136 offset1:204
	v_bfe_u32 v19, v33, 16, 1
	v_lshrrev_b32_e32 v17, 16, v17
	v_add3_u32 v19, v33, v19, s22
	v_and_or_b32 v26, v19, s23, v17
	v_add_u32_e32 v19, 0x400, v53
	ds_read2_b32 v[32:33], v19 offset0:16 offset1:84
	s_waitcnt lgkmcnt(1)
	v_bfe_u32 v17, v28, 16, 1
	v_add3_u32 v17, v28, v17, s22
	v_bfe_u32 v21, v29, 16, 1
	ds_read2_b32 v[64:65], v19 offset0:152 offset1:220
	v_lshrrev_b32_e32 v17, 16, v17
	v_add3_u32 v21, v29, v21, s22
	v_and_or_b32 v27, v21, s23, v17
	s_waitcnt lgkmcnt(1)
	v_bfe_u32 v17, v32, 16, 1
	v_add3_u32 v17, v32, v17, s22
	v_bfe_u32 v19, v33, 16, 1
	v_lshrrev_b32_e32 v17, 16, v17
	v_add3_u32 v19, v33, v19, s22
	v_and_or_b32 v28, v19, s23, v17
	s_waitcnt lgkmcnt(0)
	v_bfe_u32 v17, v64, 16, 1
	ds_read2_b32 v[32:33], v55 offset1:68
	v_add3_u32 v17, v64, v17, s22
	v_bfe_u32 v19, v65, 16, 1
	v_lshrrev_b32_e32 v17, 16, v17
	v_add3_u32 v19, v65, v19, s22
	v_and_or_b32 v29, v19, s23, v17
	v_or_b32_e32 v17, s0, v52
	v_lshlrev_b32_e32 v194, 13, v17
	v_lshl_add_u64 v[64:65], v[24:25], 0, v[194:195]
	s_waitcnt lgkmcnt(0)
	v_bfe_u32 v17, v32, 16, 1
	global_store_dwordx4 v[64:65], v[26:29], off nt
	v_add3_u32 v17, v32, v17, s22
	ds_read2_b32 v[28:29], v55 offset0:136 offset1:204
	v_bfe_u32 v19, v33, 16, 1
	v_lshrrev_b32_e32 v17, 16, v17
	v_add3_u32 v19, v33, v19, s22
	v_and_or_b32 v26, v19, s23, v17
	v_add_u32_e32 v19, 0x400, v55
	ds_read2_b32 v[32:33], v19 offset0:16 offset1:84
	s_waitcnt lgkmcnt(1)
	v_bfe_u32 v17, v28, 16, 1
	v_add3_u32 v17, v28, v17, s22
	v_bfe_u32 v21, v29, 16, 1
	ds_read2_b32 v[64:65], v19 offset0:152 offset1:220
	v_lshrrev_b32_e32 v17, 16, v17
	v_add3_u32 v21, v29, v21, s22
	v_and_or_b32 v27, v21, s23, v17
	s_waitcnt lgkmcnt(1)
	v_bfe_u32 v17, v32, 16, 1
	v_add3_u32 v17, v32, v17, s22
	v_bfe_u32 v19, v33, 16, 1
	v_lshrrev_b32_e32 v17, 16, v17
	v_add3_u32 v19, v33, v19, s22
	v_and_or_b32 v28, v19, s23, v17
	s_waitcnt lgkmcnt(0)
	v_bfe_u32 v17, v64, 16, 1
	ds_read2_b32 v[32:33], v57 offset1:68
	v_add3_u32 v17, v64, v17, s22
	v_bfe_u32 v19, v65, 16, 1
	v_lshrrev_b32_e32 v17, 16, v17
	v_add3_u32 v19, v65, v19, s22
	v_and_or_b32 v29, v19, s23, v17
	v_or_b32_e32 v17, s0, v54
	v_lshlrev_b32_e32 v194, 13, v17
	v_lshl_add_u64 v[64:65], v[24:25], 0, v[194:195]
	s_waitcnt lgkmcnt(0)
	v_bfe_u32 v17, v32, 16, 1
	global_store_dwordx4 v[64:65], v[26:29], off nt
	v_add3_u32 v17, v32, v17, s22
	ds_read2_b32 v[28:29], v57 offset0:136 offset1:204
	v_bfe_u32 v19, v33, 16, 1
	v_lshrrev_b32_e32 v17, 16, v17
	v_add3_u32 v19, v33, v19, s22
	v_and_or_b32 v26, v19, s23, v17
	v_add_u32_e32 v19, 0x400, v57
	ds_read2_b32 v[32:33], v19 offset0:16 offset1:84
	s_waitcnt lgkmcnt(1)
	v_bfe_u32 v17, v28, 16, 1
	v_add3_u32 v17, v28, v17, s22
	v_bfe_u32 v21, v29, 16, 1
	ds_read2_b32 v[64:65], v19 offset0:152 offset1:220
	v_lshrrev_b32_e32 v17, 16, v17
	v_add3_u32 v21, v29, v21, s22
	v_and_or_b32 v27, v21, s23, v17
	s_waitcnt lgkmcnt(1)
	v_bfe_u32 v17, v32, 16, 1
	v_add3_u32 v17, v32, v17, s22
	v_bfe_u32 v19, v33, 16, 1
	v_lshrrev_b32_e32 v17, 16, v17
	v_add3_u32 v19, v33, v19, s22
	v_and_or_b32 v28, v19, s23, v17
	s_waitcnt lgkmcnt(0)
	v_bfe_u32 v17, v64, 16, 1
	v_add3_u32 v17, v64, v17, s22
	v_bfe_u32 v19, v65, 16, 1
	v_lshrrev_b32_e32 v17, 16, v17
	v_add3_u32 v19, v65, v19, s22
	v_and_or_b32 v29, v19, s23, v17
	v_or_b32_e32 v17, s0, v56
	v_lshlrev_b32_e32 v194, 13, v17
	v_lshl_add_u64 v[24:25], v[24:25], 0, v[194:195]
	global_store_dwordx4 v[24:25], v[26:29], off nt
	s_waitcnt lgkmcnt(0)

.Lpb_adone:
	s_add_u32 s6, s4, 0x4000
	s_addc_u32 s7, s5, 0
	s_add_u32 s66, s40, 0x2000
	s_addc_u32 s67, s41, 0
	s_add_u32 s12, s52, s69
	s_addc_u32 s13, s53, 0
	s_add_u32 s38, s12, 0x4000
	s_addc_u32 s39, s13, 0
	s_cmp_eq_u32 s62, 0
	s_cbranch_scc1 .Lpb_l0
	s_and_b32 s68, s64, s88
	s_cmp_eq_u32 s68, 1
	s_cbranch_scc1 .Lpb_l1c
	s_sub_u32 s68, 0, s88
	s_subb_u32 s69, 0, 0
	s_not_b64 s[68:69], s[68:69]
	global_load_dwordx4 v[2:5], v178, s[4:5] nt
	global_load_dwordx4 v[6:9], v178, s[4:5] offset:1024 nt
	global_load_dwordx4 v[10:13], v178, s[4:5] offset:2048 nt
	global_load_dwordx4 v[14:17], v178, s[4:5] offset:3072 nt
	global_load_dwordx4 v[18:21], v179, s[4:5] nt
	global_load_dwordx4 v[22:25], v179, s[4:5] offset:1024 nt
	global_load_dwordx4 v[26:29], v179, s[4:5] offset:2048 nt
	global_load_dwordx4 v[30:33], v179, s[4:5] offset:3072 nt
	global_load_dwordx4 v[34:37], v180, s[4:5] nt
	global_load_dwordx4 v[38:41], v180, s[4:5] offset:1024 nt
	global_load_dwordx4 v[42:45], v180, s[4:5] offset:2048 nt
	global_load_dwordx4 v[46:49], v180, s[4:5] offset:3072 nt
	global_load_dwordx4 v[50:53], v181, s[4:5] nt
	global_load_dwordx4 v[54:57], v181, s[4:5] offset:1024 nt
	global_load_dwordx4 v[58:61], v181, s[4:5] offset:2048 nt
	global_load_dwordx4 v[62:65], v181, s[4:5] offset:3072 nt
	global_load_dwordx2 v[130:131], v182, s[40:41] nt
	global_load_dwordx2 v[132:133], v182, s[40:41] offset:512 nt
	global_load_dwordx2 v[134:135], v182, s[40:41] offset:1024 nt
	global_load_dwordx2 v[136:137], v182, s[40:41] offset:1536 nt
	global_load_dwordx2 v[138:139], v182, s[40:41] offset:2048 nt
	global_load_dwordx2 v[140:141], v182, s[40:41] offset:2560 nt
	global_load_dwordx2 v[142:143], v182, s[40:41] offset:3072 nt
	global_load_dwordx2 v[144:145], v182, s[40:41] offset:3584 nt
	global_load_dwordx2 v[146:147], v183, s[40:41] nt
	global_load_dwordx2 v[148:149], v183, s[40:41] offset:512 nt
	global_load_dwordx2 v[150:151], v183, s[40:41] offset:1024 nt
	global_load_dwordx2 v[152:153], v183, s[40:41] offset:1536 nt
	global_load_dwordx2 v[154:155], v183, s[40:41] offset:2048 nt
	global_load_dwordx2 v[156:157], v183, s[40:41] offset:2560 nt
	global_load_dwordx2 v[158:159], v183, s[40:41] offset:3072 nt
	global_load_dwordx2 v[160:161], v183, s[40:41] offset:3584 nt
	global_load_dwordx2 v[162:163], v182, s[66:67] nt
	global_load_dwordx2 v[164:165], v182, s[66:67] offset:512 nt
	global_load_dwordx2 v[166:167], v182, s[66:67] offset:1024 nt
	global_load_dwordx2 v[168:169], v182, s[66:67] offset:1536 nt
	global_load_dwordx2 v[170:171], v182, s[66:67] offset:2048 nt
	global_load_dwordx2 v[172:173], v182, s[66:67] offset:2560 nt
	global_load_dwordx2 v[174:175], v182, s[66:67] offset:3072 nt
	global_load_dwordx2 v[176:177], v182, s[66:67] offset:3584 nt
	global_load_dwordx2 v[236:237], v183, s[66:67] nt
	global_load_dwordx2 v[238:239], v183, s[66:67] offset:512 nt
	global_load_dwordx2 v[240:241], v183, s[66:67] offset:1024 nt
	global_load_dwordx2 v[242:243], v183, s[66:67] offset:1536 nt
	global_load_dwordx2 v[244:245], v183, s[66:67] offset:2048 nt
	global_load_dwordx2 v[246:247], v183, s[66:67] offset:2560 nt
	global_load_dwordx2 v[248:249], v183, s[66:67] offset:3072 nt
	global_load_dwordx2 v[250:251], v183, s[66:67] offset:3584 nt
	global_load_dwordx4 v[66:69], v178, s[6:7] nt
	s_waitcnt vmcnt(48)
	s_waitcnt vmcnt(32)
	v_lshlrev_b32_e32 v228, 16, v130
	v_and_b32_e32 v229, 0xffff0000, v130
	v_lshlrev_b32_e32 v230, 16, v131
	v_and_b32_e32 v231, 0xffff0000, v131
	v_pk_add_f32 v[2:3], v[2:3], v[228:229]
	v_pk_add_f32 v[4:5], v[4:5], v[230:231]
	v_pk_mul_f32 v[218:219], v[2:3], v[2:3]
	v_pk_fma_f32 v[218:219], v[4:5], v[4:5], v[218:219]
	v_cvt_pk_bf16_f32 v130, v2, v3
	v_cvt_pk_bf16_f32 v131, v4, v5
	s_mov_b64 exec, s[68:69]
	global_store_dwordx2 v182, v[130:131], s[40:41] nt
	s_mov_b64 exec, -1
	global_load_dwordx4 v[70:73], v178, s[6:7] offset:1024 nt
	s_waitcnt vmcnt(33)
	v_lshlrev_b32_e32 v228, 16, v132
	v_and_b32_e32 v229, 0xffff0000, v132
	v_lshlrev_b32_e32 v230, 16, v133
	v_and_b32_e32 v231, 0xffff0000, v133
	v_pk_add_f32 v[6:7], v[6:7], v[228:229]
	v_pk_add_f32 v[8:9], v[8:9], v[230:231]
	v_pk_fma_f32 v[218:219], v[6:7], v[6:7], v[218:219]
	v_pk_fma_f32 v[218:219], v[8:9], v[8:9], v[218:219]
	v_cvt_pk_bf16_f32 v132, v6, v7
	v_cvt_pk_bf16_f32 v133, v8, v9
	s_mov_b64 exec, s[68:69]
	global_store_dwordx2 v182, v[132:133], s[40:41] offset:512 nt
	s_mov_b64 exec, -1
	global_load_dwordx4 v[74:77], v178, s[6:7] offset:2048 nt
	s_waitcnt vmcnt(34)
	v_lshlrev_b32_e32 v228, 16, v134
	v_and_b32_e32 v229, 0xffff0000, v134
	v_lshlrev_b32_e32 v230, 16, v135
	v_and_b32_e32 v231, 0xffff0000, v135
	v_pk_add_f32 v[10:11], v[10:11], v[228:229]
	v_pk_add_f32 v[12:13], v[12:13], v[230:231]
	v_pk_fma_f32 v[218:219], v[10:11], v[10:11], v[218:219]
	v_pk_fma_f32 v[218:219], v[12:13], v[12:13], v[218:219]
	v_cvt_pk_bf16_f32 v134, v10, v11
	v_cvt_pk_bf16_f32 v135, v12, v13
	s_mov_b64 exec, s[68:69]
	global_store_dwordx2 v182, v[134:135], s[40:41] offset:1024 nt
	s_mov_b64 exec, -1
	global_load_dwordx4 v[78:81], v178, s[6:7] offset:3072 nt
	s_waitcnt vmcnt(35)
	v_lshlrev_b32_e32 v228, 16, v136
	v_and_b32_e32 v229, 0xffff0000, v136
	v_lshlrev_b32_e32 v230, 16, v137
	v_and_b32_e32 v231, 0xffff0000, v137
	v_pk_add_f32 v[14:15], v[14:15], v[228:229]
	v_pk_add_f32 v[16:17], v[16:17], v[230:231]
	v_pk_fma_f32 v[218:219], v[14:15], v[14:15], v[218:219]
	v_pk_fma_f32 v[218:219], v[16:17], v[16:17], v[218:219]
	v_cvt_pk_bf16_f32 v136, v14, v15
	v_cvt_pk_bf16_f32 v137, v16, v17
	s_mov_b64 exec, s[68:69]
	global_store_dwordx2 v182, v[136:137], s[40:41] offset:1536 nt
	s_mov_b64 exec, -1
	global_load_dwordx4 v[82:85], v179, s[6:7] nt
	s_waitcnt vmcnt(36)
	v_lshlrev_b32_e32 v228, 16, v138
	v_and_b32_e32 v229, 0xffff0000, v138
	v_lshlrev_b32_e32 v230, 16, v139
	v_and_b32_e32 v231, 0xffff0000, v139
	v_pk_add_f32 v[18:19], v[18:19], v[228:229]
	v_pk_add_f32 v[20:21], v[20:21], v[230:231]
	v_pk_fma_f32 v[218:219], v[18:19], v[18:19], v[218:219]
	v_pk_fma_f32 v[218:219], v[20:21], v[20:21], v[218:219]
	v_cvt_pk_bf16_f32 v138, v18, v19
	v_cvt_pk_bf16_f32 v139, v20, v21
	s_mov_b64 exec, s[68:69]
	global_store_dwordx2 v182, v[138:139], s[40:41] offset:2048 nt
	s_mov_b64 exec, -1
	global_load_dwordx4 v[86:89], v179, s[6:7] offset:1024 nt
	s_waitcnt vmcnt(37)
	v_lshlrev_b32_e32 v228, 16, v140
	v_and_b32_e32 v229, 0xffff0000, v140
	v_lshlrev_b32_e32 v230, 16, v141
	v_and_b32_e32 v231, 0xffff0000, v141
	v_pk_add_f32 v[22:23], v[22:23], v[228:229]
	v_pk_add_f32 v[24:25], v[24:25], v[230:231]
	v_pk_fma_f32 v[218:219], v[22:23], v[22:23], v[218:219]
	v_pk_fma_f32 v[218:219], v[24:25], v[24:25], v[218:219]
	v_cvt_pk_bf16_f32 v140, v22, v23
	v_cvt_pk_bf16_f32 v141, v24, v25
	s_mov_b64 exec, s[68:69]
	global_store_dwordx2 v182, v[140:141], s[40:41] offset:2560 nt
	s_mov_b64 exec, -1
	global_load_dwordx4 v[90:93], v179, s[6:7] offset:2048 nt
	s_waitcnt vmcnt(38)
	v_lshlrev_b32_e32 v228, 16, v142
	v_and_b32_e32 v229, 0xffff0000, v142
	v_lshlrev_b32_e32 v230, 16, v143
	v_and_b32_e32 v231, 0xffff0000, v143
	v_pk_add_f32 v[26:27], v[26:27], v[228:229]
	v_pk_add_f32 v[28:29], v[28:29], v[230:231]
	v_pk_fma_f32 v[218:219], v[26:27], v[26:27], v[218:219]
	v_pk_fma_f32 v[218:219], v[28:29], v[28:29], v[218:219]
	v_cvt_pk_bf16_f32 v142, v26, v27
	v_cvt_pk_bf16_f32 v143, v28, v29
	s_mov_b64 exec, s[68:69]
	global_store_dwordx2 v182, v[142:143], s[40:41] offset:3072 nt
	s_mov_b64 exec, -1
	global_load_dwordx4 v[94:97], v179, s[6:7] offset:3072 nt
	s_waitcnt vmcnt(39)
	v_lshlrev_b32_e32 v228, 16, v144
	v_and_b32_e32 v229, 0xffff0000, v144
	v_lshlrev_b32_e32 v230, 16, v145
	v_and_b32_e32 v231, 0xffff0000, v145
	v_pk_add_f32 v[30:31], v[30:31], v[228:229]
	v_pk_add_f32 v[32:33], v[32:33], v[230:231]
	v_pk_fma_f32 v[218:219], v[30:31], v[30:31], v[218:219]
	v_pk_fma_f32 v[218:219], v[32:33], v[32:33], v[218:219]
	v_cvt_pk_bf16_f32 v144, v30, v31
	v_cvt_pk_bf16_f32 v145, v32, v33
	s_mov_b64 exec, s[68:69]
	global_store_dwordx2 v182, v[144:145], s[40:41] offset:3584 nt
	s_mov_b64 exec, -1
	global_load_dwordx4 v[98:101], v180, s[6:7] nt
	s_waitcnt vmcnt(40)
	v_lshlrev_b32_e32 v228, 16, v146
	v_and_b32_e32 v229, 0xffff0000, v146
	v_lshlrev_b32_e32 v230, 16, v147
	v_and_b32_e32 v231, 0xffff0000, v147
	v_pk_add_f32 v[34:35], v[34:35], v[228:229]
	v_pk_add_f32 v[36:37], v[36:37], v[230:231]
	v_pk_fma_f32 v[218:219], v[34:35], v[34:35], v[218:219]
	v_pk_fma_f32 v[218:219], v[36:37], v[36:37], v[218:219]
	v_cvt_pk_bf16_f32 v146, v34, v35
	v_cvt_pk_bf16_f32 v147, v36, v37
	s_mov_b64 exec, s[68:69]
	global_store_dwordx2 v183, v[146:147], s[40:41] nt
	s_mov_b64 exec, -1
	global_load_dwordx4 v[102:105], v180, s[6:7] offset:1024 nt
	s_waitcnt vmcnt(41)
	v_lshlrev_b32_e32 v228, 16, v148
	v_and_b32_e32 v229, 0xffff0000, v148
	v_lshlrev_b32_e32 v230, 16, v149
	v_and_b32_e32 v231, 0xffff0000, v149
	v_pk_add_f32 v[38:39], v[38:39], v[228:229]
	v_pk_add_f32 v[40:41], v[40:41], v[230:231]
	v_pk_fma_f32 v[218:219], v[38:39], v[38:39], v[218:219]
	v_pk_fma_f32 v[218:219], v[40:41], v[40:41], v[218:219]
	v_cvt_pk_bf16_f32 v148, v38, v39
	v_cvt_pk_bf16_f32 v149, v40, v41
	s_mov_b64 exec, s[68:69]
	global_store_dwordx2 v183, v[148:149], s[40:41] offset:512 nt
	s_mov_b64 exec, -1
	global_load_dwordx4 v[106:109], v180, s[6:7] offset:2048 nt
	s_waitcnt vmcnt(42)
	v_lshlrev_b32_e32 v228, 16, v150
	v_and_b32_e32 v229, 0xffff0000, v150
	v_lshlrev_b32_e32 v230, 16, v151
	v_and_b32_e32 v231, 0xffff0000, v151
	v_pk_add_f32 v[42:43], v[42:43], v[228:229]
	v_pk_add_f32 v[44:45], v[44:45], v[230:231]
	v_pk_fma_f32 v[218:219], v[42:43], v[42:43], v[218:219]
	v_pk_fma_f32 v[218:219], v[44:45], v[44:45], v[218:219]
	v_cvt_pk_bf16_f32 v150, v42, v43
	v_cvt_pk_bf16_f32 v151, v44, v45
	s_mov_b64 exec, s[68:69]
	global_store_dwordx2 v183, v[150:151], s[40:41] offset:1024 nt
	s_mov_b64 exec, -1
	global_load_dwordx4 v[110:113], v180, s[6:7] offset:3072 nt
	s_waitcnt vmcnt(43)
	v_lshlrev_b32_e32 v228, 16, v152
	v_and_b32_e32 v229, 0xffff0000, v152
	v_lshlrev_b32_e32 v230, 16, v153
	v_and_b32_e32 v231, 0xffff0000, v153
	v_pk_add_f32 v[46:47], v[46:47], v[228:229]
	v_pk_add_f32 v[48:49], v[48:49], v[230:231]
	v_pk_fma_f32 v[218:219], v[46:47], v[46:47], v[218:219]
	v_pk_fma_f32 v[218:219], v[48:49], v[48:49], v[218:219]
	v_cvt_pk_bf16_f32 v152, v46, v47
	v_cvt_pk_bf16_f32 v153, v48, v49
	s_mov_b64 exec, s[68:69]
	global_store_dwordx2 v183, v[152:153], s[40:41] offset:1536 nt
	s_mov_b64 exec, -1
	global_load_dwordx4 v[114:117], v181, s[6:7] nt
	s_waitcnt vmcnt(44)
	v_lshlrev_b32_e32 v228, 16, v154
	v_and_b32_e32 v229, 0xffff0000, v154
	v_lshlrev_b32_e32 v230, 16, v155
	v_and_b32_e32 v231, 0xffff0000, v155
	v_pk_add_f32 v[50:51], v[50:51], v[228:229]
	v_pk_add_f32 v[52:53], v[52:53], v[230:231]
	v_pk_fma_f32 v[218:219], v[50:51], v[50:51], v[218:219]
	v_pk_fma_f32 v[218:219], v[52:53], v[52:53], v[218:219]
	v_cvt_pk_bf16_f32 v154, v50, v51
	v_cvt_pk_bf16_f32 v155, v52, v53
	s_mov_b64 exec, s[68:69]
	global_store_dwordx2 v183, v[154:155], s[40:41] offset:2048 nt
	s_mov_b64 exec, -1
	global_load_dwordx4 v[118:121], v181, s[6:7] offset:1024 nt
	s_waitcnt vmcnt(45)
	v_lshlrev_b32_e32 v228, 16, v156
	v_and_b32_e32 v229, 0xffff0000, v156
	v_lshlrev_b32_e32 v230, 16, v157
	v_and_b32_e32 v231, 0xffff0000, v157
	v_pk_add_f32 v[54:55], v[54:55], v[228:229]
	v_pk_add_f32 v[56:57], v[56:57], v[230:231]
	v_pk_fma_f32 v[218:219], v[54:55], v[54:55], v[218:219]
	v_pk_fma_f32 v[218:219], v[56:57], v[56:57], v[218:219]
	v_cvt_pk_bf16_f32 v156, v54, v55
	v_cvt_pk_bf16_f32 v157, v56, v57
	s_mov_b64 exec, s[68:69]
	global_store_dwordx2 v183, v[156:157], s[40:41] offset:2560 nt
	s_mov_b64 exec, -1
	global_load_dwordx4 v[122:125], v181, s[6:7] offset:2048 nt
	s_waitcnt vmcnt(46)
	v_lshlrev_b32_e32 v228, 16, v158
	v_and_b32_e32 v229, 0xffff0000, v158
	v_lshlrev_b32_e32 v230, 16, v159
	v_and_b32_e32 v231, 0xffff0000, v159
	v_pk_add_f32 v[58:59], v[58:59], v[228:229]
	v_pk_add_f32 v[60:61], v[60:61], v[230:231]
	v_pk_fma_f32 v[218:219], v[58:59], v[58:59], v[218:219]
	v_pk_fma_f32 v[218:219], v[60:61], v[60:61], v[218:219]
	v_cvt_pk_bf16_f32 v158, v58, v59
	v_cvt_pk_bf16_f32 v159, v60, v61
	s_mov_b64 exec, s[68:69]
	global_store_dwordx2 v183, v[158:159], s[40:41] offset:3072 nt
	s_mov_b64 exec, -1
	global_load_dwordx4 v[126:129], v181, s[6:7] offset:3072 nt
	s_waitcnt vmcnt(47)
	v_lshlrev_b32_e32 v228, 16, v160
	v_and_b32_e32 v229, 0xffff0000, v160
	v_lshlrev_b32_e32 v230, 16, v161
	v_and_b32_e32 v231, 0xffff0000, v161
	v_pk_add_f32 v[62:63], v[62:63], v[228:229]
	v_pk_add_f32 v[64:65], v[64:65], v[230:231]
	v_pk_fma_f32 v[218:219], v[62:63], v[62:63], v[218:219]
	v_pk_fma_f32 v[218:219], v[64:65], v[64:65], v[218:219]
	v_cvt_pk_bf16_f32 v160, v62, v63
	v_cvt_pk_bf16_f32 v161, v64, v65
	s_mov_b64 exec, s[68:69]
	global_store_dwordx2 v183, v[160:161], s[40:41] offset:3584 nt
	s_mov_b64 exec, -1
	s_waitcnt vmcnt(31)
	v_lshlrev_b32_e32 v228, 16, v162
	v_and_b32_e32 v229, 0xffff0000, v162
	v_lshlrev_b32_e32 v230, 16, v163
	v_and_b32_e32 v231, 0xffff0000, v163
	v_pk_add_f32 v[66:67], v[66:67], v[228:229]
	v_pk_add_f32 v[68:69], v[68:69], v[230:231]
	v_pk_mul_f32 v[220:221], v[66:67], v[66:67]
	v_pk_fma_f32 v[220:221], v[68:69], v[68:69], v[220:221]
	v_cvt_pk_bf16_f32 v162, v66, v67
	v_cvt_pk_bf16_f32 v163, v68, v69
	s_mov_b64 exec, s[68:69]
	global_store_dwordx2 v182, v[162:163], s[66:67] nt
	s_mov_b64 exec, -1
	s_waitcnt vmcnt(30)
	v_lshlrev_b32_e32 v228, 16, v164
	v_and_b32_e32 v229, 0xffff0000, v164
	v_lshlrev_b32_e32 v230, 16, v165
	v_and_b32_e32 v231, 0xffff0000, v165
	v_pk_add_f32 v[70:71], v[70:71], v[228:229]
	v_pk_add_f32 v[72:73], v[72:73], v[230:231]
	v_pk_fma_f32 v[220:221], v[70:71], v[70:71], v[220:221]
	v_pk_fma_f32 v[220:221], v[72:73], v[72:73], v[220:221]
	v_cvt_pk_bf16_f32 v164, v70, v71
	v_cvt_pk_bf16_f32 v165, v72, v73
	s_mov_b64 exec, s[68:69]
	global_store_dwordx2 v182, v[164:165], s[66:67] offset:512 nt
	s_mov_b64 exec, -1
	s_waitcnt vmcnt(29)
	v_lshlrev_b32_e32 v228, 16, v166
	v_and_b32_e32 v229, 0xffff0000, v166
	v_lshlrev_b32_e32 v230, 16, v167
	v_and_b32_e32 v231, 0xffff0000, v167
	v_pk_add_f32 v[74:75], v[74:75], v[228:229]
	v_pk_add_f32 v[76:77], v[76:77], v[230:231]
	v_pk_fma_f32 v[220:221], v[74:75], v[74:75], v[220:221]
	v_pk_fma_f32 v[220:221], v[76:77], v[76:77], v[220:221]
	v_cvt_pk_bf16_f32 v166, v74, v75
	v_cvt_pk_bf16_f32 v167, v76, v77
	s_mov_b64 exec, s[68:69]
	global_store_dwordx2 v182, v[166:167], s[66:67] offset:1024 nt
	s_mov_b64 exec, -1
	s_waitcnt vmcnt(28)
	v_lshlrev_b32_e32 v228, 16, v168
	v_and_b32_e32 v229, 0xffff0000, v168
	v_lshlrev_b32_e32 v230, 16, v169
	v_and_b32_e32 v231, 0xffff0000, v169
	v_pk_add_f32 v[78:79], v[78:79], v[228:229]
	v_pk_add_f32 v[80:81], v[80:81], v[230:231]
	v_pk_fma_f32 v[220:221], v[78:79], v[78:79], v[220:221]
	v_pk_fma_f32 v[220:221], v[80:81], v[80:81], v[220:221]
	v_cvt_pk_bf16_f32 v168, v78, v79
	v_cvt_pk_bf16_f32 v169, v80, v81
	s_mov_b64 exec, s[68:69]
	global_store_dwordx2 v182, v[168:169], s[66:67] offset:1536 nt
	s_mov_b64 exec, -1
	s_waitcnt vmcnt(27)
	v_lshlrev_b32_e32 v228, 16, v170
	v_and_b32_e32 v229, 0xffff0000, v170
	v_lshlrev_b32_e32 v230, 16, v171
	v_and_b32_e32 v231, 0xffff0000, v171
	v_pk_add_f32 v[82:83], v[82:83], v[228:229]
	v_pk_add_f32 v[84:85], v[84:85], v[230:231]
	v_pk_fma_f32 v[220:221], v[82:83], v[82:83], v[220:221]
	v_pk_fma_f32 v[220:221], v[84:85], v[84:85], v[220:221]
	v_cvt_pk_bf16_f32 v170, v82, v83
	v_cvt_pk_bf16_f32 v171, v84, v85
	s_mov_b64 exec, s[68:69]
	global_store_dwordx2 v182, v[170:171], s[66:67] offset:2048 nt
	s_mov_b64 exec, -1
	s_waitcnt vmcnt(26)
	v_lshlrev_b32_e32 v228, 16, v172
	v_and_b32_e32 v229, 0xffff0000, v172
	v_lshlrev_b32_e32 v230, 16, v173
	v_and_b32_e32 v231, 0xffff0000, v173
	v_pk_add_f32 v[86:87], v[86:87], v[228:229]
	v_pk_add_f32 v[88:89], v[88:89], v[230:231]
	v_pk_fma_f32 v[220:221], v[86:87], v[86:87], v[220:221]
	v_pk_fma_f32 v[220:221], v[88:89], v[88:89], v[220:221]
	v_cvt_pk_bf16_f32 v172, v86, v87
	v_cvt_pk_bf16_f32 v173, v88, v89
	s_mov_b64 exec, s[68:69]
	global_store_dwordx2 v182, v[172:173], s[66:67] offset:2560 nt
	s_mov_b64 exec, -1
	s_waitcnt vmcnt(25)
	v_lshlrev_b32_e32 v228, 16, v174
	v_and_b32_e32 v229, 0xffff0000, v174
	v_lshlrev_b32_e32 v230, 16, v175
	v_and_b32_e32 v231, 0xffff0000, v175
	v_pk_add_f32 v[90:91], v[90:91], v[228:229]
	v_pk_add_f32 v[92:93], v[92:93], v[230:231]
	v_pk_fma_f32 v[220:221], v[90:91], v[90:91], v[220:221]
	v_pk_fma_f32 v[220:221], v[92:93], v[92:93], v[220:221]
	v_cvt_pk_bf16_f32 v174, v90, v91
	v_cvt_pk_bf16_f32 v175, v92, v93
	s_mov_b64 exec, s[68:69]
	global_store_dwordx2 v182, v[174:175], s[66:67] offset:3072 nt
	s_mov_b64 exec, -1
	s_waitcnt vmcnt(24)
	v_lshlrev_b32_e32 v228, 16, v176
	v_and_b32_e32 v229, 0xffff0000, v176
	v_lshlrev_b32_e32 v230, 16, v177
	v_and_b32_e32 v231, 0xffff0000, v177
	v_pk_add_f32 v[94:95], v[94:95], v[228:229]
	v_pk_add_f32 v[96:97], v[96:97], v[230:231]
	v_pk_fma_f32 v[220:221], v[94:95], v[94:95], v[220:221]
	v_pk_fma_f32 v[220:221], v[96:97], v[96:97], v[220:221]
	v_cvt_pk_bf16_f32 v176, v94, v95
	v_cvt_pk_bf16_f32 v177, v96, v97
	s_mov_b64 exec, s[68:69]
	global_store_dwordx2 v182, v[176:177], s[66:67] offset:3584 nt
	s_mov_b64 exec, -1
	s_waitcnt vmcnt(23)
	v_lshlrev_b32_e32 v228, 16, v236
	v_and_b32_e32 v229, 0xffff0000, v236
	v_lshlrev_b32_e32 v230, 16, v237
	v_and_b32_e32 v231, 0xffff0000, v237
	v_pk_add_f32 v[98:99], v[98:99], v[228:229]
	v_pk_add_f32 v[100:101], v[100:101], v[230:231]
	v_pk_fma_f32 v[220:221], v[98:99], v[98:99], v[220:221]
	v_pk_fma_f32 v[220:221], v[100:101], v[100:101], v[220:221]
	v_cvt_pk_bf16_f32 v236, v98, v99
	v_cvt_pk_bf16_f32 v237, v100, v101
	s_mov_b64 exec, s[68:69]
	global_store_dwordx2 v183, v[236:237], s[66:67] nt
	s_mov_b64 exec, -1
	s_waitcnt vmcnt(22)
	v_lshlrev_b32_e32 v228, 16, v238
	v_and_b32_e32 v229, 0xffff0000, v238
	v_lshlrev_b32_e32 v230, 16, v239
	v_and_b32_e32 v231, 0xffff0000, v239
	v_pk_add_f32 v[102:103], v[102:103], v[228:229]
	v_pk_add_f32 v[104:105], v[104:105], v[230:231]
	v_pk_fma_f32 v[220:221], v[102:103], v[102:103], v[220:221]
	v_pk_fma_f32 v[220:221], v[104:105], v[104:105], v[220:221]
	v_cvt_pk_bf16_f32 v238, v102, v103
	v_cvt_pk_bf16_f32 v239, v104, v105
	s_mov_b64 exec, s[68:69]
	global_store_dwordx2 v183, v[238:239], s[66:67] offset:512 nt
	s_mov_b64 exec, -1
	s_waitcnt vmcnt(21)
	v_lshlrev_b32_e32 v228, 16, v240
	v_and_b32_e32 v229, 0xffff0000, v240
	v_lshlrev_b32_e32 v230, 16, v241
	v_and_b32_e32 v231, 0xffff0000, v241
	v_pk_add_f32 v[106:107], v[106:107], v[228:229]
	v_pk_add_f32 v[108:109], v[108:109], v[230:231]
	v_pk_fma_f32 v[220:221], v[106:107], v[106:107], v[220:221]
	v_pk_fma_f32 v[220:221], v[108:109], v[108:109], v[220:221]
	v_cvt_pk_bf16_f32 v240, v106, v107
	v_cvt_pk_bf16_f32 v241, v108, v109
	s_mov_b64 exec, s[68:69]
	global_store_dwordx2 v183, v[240:241], s[66:67] offset:1024 nt
	s_mov_b64 exec, -1
	s_waitcnt vmcnt(20)
	v_lshlrev_b32_e32 v228, 16, v242
	v_and_b32_e32 v229, 0xffff0000, v242
	v_lshlrev_b32_e32 v230, 16, v243
	v_and_b32_e32 v231, 0xffff0000, v243
	v_pk_add_f32 v[110:111], v[110:111], v[228:229]
	v_pk_add_f32 v[112:113], v[112:113], v[230:231]
	v_pk_fma_f32 v[220:221], v[110:111], v[110:111], v[220:221]
	v_pk_fma_f32 v[220:221], v[112:113], v[112:113], v[220:221]
	v_cvt_pk_bf16_f32 v242, v110, v111
	v_cvt_pk_bf16_f32 v243, v112, v113
	s_mov_b64 exec, s[68:69]
	global_store_dwordx2 v183, v[242:243], s[66:67] offset:1536 nt
	s_mov_b64 exec, -1
	s_waitcnt vmcnt(19)
	v_lshlrev_b32_e32 v228, 16, v244
	v_and_b32_e32 v229, 0xffff0000, v244
	v_lshlrev_b32_e32 v230, 16, v245
	v_and_b32_e32 v231, 0xffff0000, v245
	v_pk_add_f32 v[114:115], v[114:115], v[228:229]
	v_pk_add_f32 v[116:117], v[116:117], v[230:231]
	v_pk_fma_f32 v[220:221], v[114:115], v[114:115], v[220:221]
	v_pk_fma_f32 v[220:221], v[116:117], v[116:117], v[220:221]
	v_cvt_pk_bf16_f32 v244, v114, v115
	v_cvt_pk_bf16_f32 v245, v116, v117
	s_mov_b64 exec, s[68:69]
	global_store_dwordx2 v183, v[244:245], s[66:67] offset:2048 nt
	s_mov_b64 exec, -1
	s_waitcnt vmcnt(18)
	v_lshlrev_b32_e32 v228, 16, v246
	v_and_b32_e32 v229, 0xffff0000, v246
	v_lshlrev_b32_e32 v230, 16, v247
	v_and_b32_e32 v231, 0xffff0000, v247
	v_pk_add_f32 v[118:119], v[118:119], v[228:229]
	v_pk_add_f32 v[120:121], v[120:121], v[230:231]
	v_pk_fma_f32 v[220:221], v[118:119], v[118:119], v[220:221]
	v_pk_fma_f32 v[220:221], v[120:121], v[120:121], v[220:221]
	v_cvt_pk_bf16_f32 v246, v118, v119
	v_cvt_pk_bf16_f32 v247, v120, v121
	s_mov_b64 exec, s[68:69]
	global_store_dwordx2 v183, v[246:247], s[66:67] offset:2560 nt
	s_mov_b64 exec, -1
	s_waitcnt vmcnt(17)
	v_lshlrev_b32_e32 v228, 16, v248
	v_and_b32_e32 v229, 0xffff0000, v248
	v_lshlrev_b32_e32 v230, 16, v249
	v_and_b32_e32 v231, 0xffff0000, v249
	v_pk_add_f32 v[122:123], v[122:123], v[228:229]
	v_pk_add_f32 v[124:125], v[124:125], v[230:231]
	v_pk_fma_f32 v[220:221], v[122:123], v[122:123], v[220:221]
	v_pk_fma_f32 v[220:221], v[124:125], v[124:125], v[220:221]
	v_cvt_pk_bf16_f32 v248, v122, v123
	v_cvt_pk_bf16_f32 v249, v124, v125
	s_mov_b64 exec, s[68:69]
	global_store_dwordx2 v183, v[248:249], s[66:67] offset:3072 nt
	s_mov_b64 exec, -1
	s_waitcnt vmcnt(16)
	v_lshlrev_b32_e32 v228, 16, v250
	v_and_b32_e32 v229, 0xffff0000, v250
	v_lshlrev_b32_e32 v230, 16, v251
	v_and_b32_e32 v231, 0xffff0000, v251
	v_pk_add_f32 v[126:127], v[126:127], v[228:229]
	v_pk_add_f32 v[128:129], v[128:129], v[230:231]
	v_pk_fma_f32 v[220:221], v[126:127], v[126:127], v[220:221]
	v_pk_fma_f32 v[220:221], v[128:129], v[128:129], v[220:221]
	v_cvt_pk_bf16_f32 v250, v126, v127
	v_cvt_pk_bf16_f32 v251, v128, v129
	s_mov_b64 exec, s[68:69]
	global_store_dwordx2 v183, v[250:251], s[66:67] offset:3584 nt
	s_mov_b64 exec, -1
	s_branch .Lpb_sums
